# v18: v15 + squared-ReLU MLP epilogue packs bf16 with v_cvt_pk_bf16_f32 (same round-to-nearest-even) instead of the bfe/add3/perm sequence: 8 VALU per 4 values instead of 20
# speedup vs baseline: 1.0131x; 1.0056x over previous
.LBB0_2585:
	ds_read_b128 v[140:143], v149
	ds_read_b128 v[152:155], v149 offset:1024
	ds_read_b128 v[156:159], v149 offset:2048
	ds_read_b128 v[160:163], v149 offset:3072
	s_add_i32 s78, s42, 2
	s_add_u32 s43, s40, 0xfff80080
	s_addc_u32 s44, s41, -1
	s_cmp_eq_u32 s75, s42
	s_cselect_b32 s42, s74, s76
	s_cselect_b32 s45, s31, s44
	s_cselect_b32 s44, s39, s43
	s_cselect_b32 s43, s29, s77
	v_lshl_add_u64 v[144:145], s[40:41], 0, v[132:133]
	s_add_i32 m0, s50, 0xc000
	ds_read_b128 v[164:167], v150
	ds_read_b128 v[168:171], v150 offset:1024
	ds_read_b128 v[172:175], v150 offset:2048
	ds_read_b128 v[176:179], v150 offset:3072
	ds_read_b128 v[180:183], v150 offset:4096
	ds_read_b128 v[184:187], v150 offset:5120
	ds_read_b128 v[188:191], v150 offset:6144
	ds_read_b128 v[192:195], v150 offset:7168
	global_load_lds_dwordx4 v[144:145], off
	v_lshl_add_u64 v[144:145], s[40:41], 0, v[134:135]
	s_add_i32 m0, s50, 0xe000
	s_nop 0
	global_load_lds_dwordx4 v[144:145], off
	s_waitcnt lgkmcnt(8)
	s_barrier
	s_waitcnt lgkmcnt(0)
	s_setprio 1
	s_waitcnt lgkmcnt(0)
	v_mfma_f32_16x16x32_bf16 v[124:127], v[140:143], v[164:167], v[124:127]
	v_mfma_f32_16x16x32_bf16 v[120:123], v[156:159], v[164:167], v[120:123]
	v_mfma_f32_16x16x32_bf16 v[116:119], v[140:143], v[172:175], v[116:119]
	v_mfma_f32_16x16x32_bf16 v[112:115], v[156:159], v[172:175], v[112:115]
	v_mfma_f32_16x16x32_bf16 v[100:103], v[140:143], v[180:183], v[100:103]
	v_mfma_f32_16x16x32_bf16 v[96:99], v[156:159], v[180:183], v[96:99]
	v_mfma_f32_16x16x32_bf16 v[84:87], v[140:143], v[188:191], v[84:87]
	v_mfma_f32_16x16x32_bf16 v[80:83], v[156:159], v[188:191], v[80:83]
	v_mfma_f32_16x16x32_bf16 v[124:127], v[152:155], v[168:171], v[124:127]
	v_mfma_f32_16x16x32_bf16 v[120:123], v[160:163], v[168:171], v[120:123]
	v_mfma_f32_16x16x32_bf16 v[116:119], v[152:155], v[176:179], v[116:119]
	v_mfma_f32_16x16x32_bf16 v[112:115], v[160:163], v[176:179], v[112:115]
	v_mfma_f32_16x16x32_bf16 v[100:103], v[152:155], v[184:187], v[100:103]
	v_mfma_f32_16x16x32_bf16 v[96:99], v[160:163], v[184:187], v[96:99]
	v_mfma_f32_16x16x32_bf16 v[84:87], v[152:155], v[192:195], v[84:87]
	v_mfma_f32_16x16x32_bf16 v[80:83], v[160:163], v[192:195], v[80:83]
	s_setprio 0
	s_barrier
	s_add_i32 s79, s62, s49
	v_lshl_add_u64 v[144:145], s[42:43], 0, v[128:129]
	s_mov_b32 m0, s79
	ds_read_b128 v[196:199], v151
	ds_read_b128 v[200:203], v151 offset:1024
	ds_read_b128 v[204:207], v151 offset:2048
	ds_read_b128 v[208:211], v151 offset:3072
	global_load_lds_dwordx4 v[144:145], off
	v_lshl_add_u64 v[212:213], s[42:43], 0, v[130:131]
	s_add_i32 m0, s79, 0x2000
	s_nop 0
	global_load_lds_dwordx4 v[212:213], off
	s_barrier
	s_waitcnt lgkmcnt(0)
	s_setprio 1
	s_waitcnt lgkmcnt(0)
	v_mfma_f32_16x16x32_bf16 v[108:111], v[196:199], v[164:167], v[108:111]
	v_mfma_f32_16x16x32_bf16 v[104:107], v[204:207], v[164:167], v[104:107]
	v_mfma_f32_16x16x32_bf16 v[92:95], v[196:199], v[172:175], v[92:95]
	v_mfma_f32_16x16x32_bf16 v[88:91], v[204:207], v[172:175], v[88:91]
	v_mfma_f32_16x16x32_bf16 v[76:79], v[196:199], v[180:183], v[76:79]
	v_mfma_f32_16x16x32_bf16 v[72:75], v[204:207], v[180:183], v[72:75]
	v_mfma_f32_16x16x32_bf16 v[68:71], v[196:199], v[188:191], v[68:71]
	v_mfma_f32_16x16x32_bf16 v[64:67], v[204:207], v[188:191], v[64:67]
	v_mfma_f32_16x16x32_bf16 v[108:111], v[200:203], v[168:171], v[108:111]
	v_mfma_f32_16x16x32_bf16 v[104:107], v[208:211], v[168:171], v[104:107]
	v_mfma_f32_16x16x32_bf16 v[92:95], v[200:203], v[176:179], v[92:95]
	v_mfma_f32_16x16x32_bf16 v[88:91], v[208:211], v[176:179], v[88:91]
	v_mfma_f32_16x16x32_bf16 v[76:79], v[200:203], v[184:187], v[76:79]
	v_mfma_f32_16x16x32_bf16 v[72:75], v[208:211], v[184:187], v[72:75]
	v_mfma_f32_16x16x32_bf16 v[68:71], v[200:203], v[192:195], v[68:71]
	v_mfma_f32_16x16x32_bf16 v[64:67], v[208:211], v[192:195], v[64:67]
	s_setprio 0
	s_mov_b32 m0, s50
	v_lshl_add_u64 v[214:215], s[44:45], 0, v[128:129]
	s_barrier
	ds_read_b128 v[164:167], v150 offset:16384
	ds_read_b128 v[168:171], v150 offset:17408
	ds_read_b128 v[172:175], v150 offset:18432
	ds_read_b128 v[176:179], v150 offset:19456
	ds_read_b128 v[180:183], v150 offset:20480
	ds_read_b128 v[184:187], v150 offset:21504
	ds_read_b128 v[188:191], v150 offset:22528
	ds_read_b128 v[192:195], v150 offset:23552
	global_load_lds_dwordx4 v[214:215], off
	v_lshl_add_u64 v[218:219], s[44:45], 0, v[130:131]
	s_mov_b32 m0, s51
	s_nop 0
	global_load_lds_dwordx4 v[218:219], off
	s_barrier
	s_waitcnt lgkmcnt(0)
	s_setprio 1
	s_waitcnt lgkmcnt(0)
	v_mfma_f32_16x16x32_bf16 v[60:63], v[140:143], v[164:167], v[60:63]
	v_mfma_f32_16x16x32_bf16 v[56:59], v[156:159], v[164:167], v[56:59]
	v_mfma_f32_16x16x32_bf16 v[52:55], v[140:143], v[172:175], v[52:55]
	v_mfma_f32_16x16x32_bf16 v[48:51], v[156:159], v[172:175], v[48:51]
	v_mfma_f32_16x16x32_bf16 v[40:43], v[140:143], v[180:183], v[40:43]
	v_mfma_f32_16x16x32_bf16 v[32:35], v[156:159], v[180:183], v[32:35]
	v_mfma_f32_16x16x32_bf16 v[24:27], v[140:143], v[188:191], v[24:27]
	v_mfma_f32_16x16x32_bf16 v[16:19], v[156:159], v[188:191], v[16:19]
	v_mfma_f32_16x16x32_bf16 v[60:63], v[152:155], v[168:171], v[60:63]
	v_mfma_f32_16x16x32_bf16 v[56:59], v[160:163], v[168:171], v[56:59]
	v_mfma_f32_16x16x32_bf16 v[52:55], v[152:155], v[176:179], v[52:55]
	v_mfma_f32_16x16x32_bf16 v[48:51], v[160:163], v[176:179], v[48:51]
	v_mfma_f32_16x16x32_bf16 v[40:43], v[152:155], v[184:187], v[40:43]
	v_mfma_f32_16x16x32_bf16 v[32:35], v[160:163], v[184:187], v[32:35]
	v_mfma_f32_16x16x32_bf16 v[24:27], v[152:155], v[192:195], v[24:27]
	v_mfma_f32_16x16x32_bf16 v[16:19], v[160:163], v[192:195], v[16:19]
	s_setprio 0
	s_barrier
	s_add_u32 s80, s42, 0x80000
	s_addc_u32 s81, s43, 0
	s_add_i32 s79, s63, s49
	v_lshl_add_u64 v[140:141], s[80:81], 0, v[128:129]
	s_mov_b32 m0, s79
	s_nop 0
	global_load_lds_dwordx4 v[140:141], off
	v_lshl_add_u64 v[140:141], s[80:81], 0, v[130:131]
	s_add_i32 m0, s79, 0x2000
	s_nop 0
	global_load_lds_dwordx4 v[140:141], off
	s_waitcnt vmcnt(6)
	s_barrier
	s_setprio 1
	v_mfma_f32_16x16x32_bf16 v[44:47], v[196:199], v[164:167], v[44:47]
	v_mfma_f32_16x16x32_bf16 v[36:39], v[204:207], v[164:167], v[36:39]
	v_mfma_f32_16x16x32_bf16 v[28:31], v[196:199], v[172:175], v[28:31]
	v_mfma_f32_16x16x32_bf16 v[20:23], v[204:207], v[172:175], v[20:23]
	v_mfma_f32_16x16x32_bf16 v[12:15], v[196:199], v[180:183], v[12:15]
	v_mfma_f32_16x16x32_bf16 v[8:11], v[204:207], v[180:183], v[8:11]
	v_mfma_f32_16x16x32_bf16 v[4:7], v[196:199], v[188:191], v[4:7]
	v_mfma_f32_16x16x32_bf16 v[0:3], v[204:207], v[188:191], v[0:3]
	v_mfma_f32_16x16x32_bf16 v[44:47], v[200:203], v[168:171], v[44:47]
	v_mfma_f32_16x16x32_bf16 v[36:39], v[208:211], v[168:171], v[36:39]
	v_mfma_f32_16x16x32_bf16 v[28:31], v[200:203], v[176:179], v[28:31]
	v_mfma_f32_16x16x32_bf16 v[20:23], v[208:211], v[176:179], v[20:23]
	v_mfma_f32_16x16x32_bf16 v[12:15], v[200:203], v[184:187], v[12:15]
	v_mfma_f32_16x16x32_bf16 v[8:11], v[208:211], v[184:187], v[8:11]
	v_mfma_f32_16x16x32_bf16 v[4:7], v[200:203], v[192:195], v[4:7]
	v_mfma_f32_16x16x32_bf16 v[0:3], v[208:211], v[192:195], v[0:3]
	s_setprio 0
	s_add_i32 s79, 0, 0x18000
	v_add_u32_e32 v160, s79, v148
	s_barrier
	ds_read_b128 v[140:143], v160
	ds_read_b128 v[152:155], v160 offset:1024
	ds_read_b128 v[156:159], v160 offset:2048
	ds_read_b128 v[160:163], v160 offset:3072
	s_add_u32 s44, s44, 0x80000
	s_addc_u32 s45, s45, 0
	s_mov_b32 m0, s52
	v_lshl_add_u64 v[196:197], s[44:45], 0, v[128:129]
	ds_read_b128 v[164:167], v150 offset:32768
	ds_read_b128 v[168:171], v150 offset:33792
	ds_read_b128 v[172:175], v150 offset:34816
	ds_read_b128 v[176:179], v150 offset:35840
	ds_read_b128 v[180:183], v150 offset:36864
	ds_read_b128 v[184:187], v150 offset:37888
	ds_read_b128 v[188:191], v150 offset:38912
	ds_read_b128 v[192:195], v150 offset:39936
	global_load_lds_dwordx4 v[196:197], off
	v_lshl_add_u64 v[196:197], s[44:45], 0, v[130:131]
	s_mov_b32 m0, s53
	s_nop 0
	global_load_lds_dwordx4 v[196:197], off
	s_waitcnt lgkmcnt(8)
	s_barrier
	s_waitcnt lgkmcnt(0)
	s_setprio 1
	s_waitcnt lgkmcnt(0)
	v_mfma_f32_16x16x32_bf16 v[124:127], v[140:143], v[164:167], v[124:127]
	v_mfma_f32_16x16x32_bf16 v[120:123], v[156:159], v[164:167], v[120:123]
	v_mfma_f32_16x16x32_bf16 v[116:119], v[140:143], v[172:175], v[116:119]
	v_mfma_f32_16x16x32_bf16 v[112:115], v[156:159], v[172:175], v[112:115]
	v_mfma_f32_16x16x32_bf16 v[100:103], v[140:143], v[180:183], v[100:103]
	v_mfma_f32_16x16x32_bf16 v[96:99], v[156:159], v[180:183], v[96:99]
	v_mfma_f32_16x16x32_bf16 v[84:87], v[140:143], v[188:191], v[84:87]
	v_mfma_f32_16x16x32_bf16 v[80:83], v[156:159], v[188:191], v[80:83]
	v_mfma_f32_16x16x32_bf16 v[124:127], v[152:155], v[168:171], v[124:127]
	v_mfma_f32_16x16x32_bf16 v[120:123], v[160:163], v[168:171], v[120:123]
	v_mfma_f32_16x16x32_bf16 v[116:119], v[152:155], v[176:179], v[116:119]
	v_mfma_f32_16x16x32_bf16 v[112:115], v[160:163], v[176:179], v[112:115]
	v_mfma_f32_16x16x32_bf16 v[100:103], v[152:155], v[184:187], v[100:103]
	v_mfma_f32_16x16x32_bf16 v[96:99], v[160:163], v[184:187], v[96:99]
	v_mfma_f32_16x16x32_bf16 v[84:87], v[152:155], v[192:195], v[84:87]
	v_mfma_f32_16x16x32_bf16 v[80:83], v[160:163], v[192:195], v[80:83]
	s_setprio 0
	s_barrier
	s_add_i32 s44, 0, 0x1c000
	s_add_i32 s45, s79, s49
	v_add_u32_e32 v208, s44, v148
	v_lshl_add_u64 v[144:145], v[144:145], 0, s[10:11]
	s_mov_b32 m0, s45
	ds_read_b128 v[196:199], v208
	ds_read_b128 v[200:203], v208 offset:1024
	ds_read_b128 v[204:207], v208 offset:2048
	ds_read_b128 v[208:211], v208 offset:3072
	global_load_lds_dwordx4 v[144:145], off
	v_lshl_add_u64 v[144:145], v[212:213], 0, s[10:11]
	s_add_i32 m0, s45, 0x2000
	s_nop 0
	global_load_lds_dwordx4 v[144:145], off
	s_barrier
	s_waitcnt lgkmcnt(0)
	s_setprio 1
	s_waitcnt lgkmcnt(0)
	v_mfma_f32_16x16x32_bf16 v[108:111], v[196:199], v[164:167], v[108:111]
	v_mfma_f32_16x16x32_bf16 v[104:107], v[204:207], v[164:167], v[104:107]
	v_mfma_f32_16x16x32_bf16 v[92:95], v[196:199], v[172:175], v[92:95]
	v_mfma_f32_16x16x32_bf16 v[88:91], v[204:207], v[172:175], v[88:91]
	v_mfma_f32_16x16x32_bf16 v[76:79], v[196:199], v[180:183], v[76:79]
	v_mfma_f32_16x16x32_bf16 v[72:75], v[204:207], v[180:183], v[72:75]
	v_mfma_f32_16x16x32_bf16 v[68:71], v[196:199], v[188:191], v[68:71]
	v_mfma_f32_16x16x32_bf16 v[64:67], v[204:207], v[188:191], v[64:67]
	v_mfma_f32_16x16x32_bf16 v[108:111], v[200:203], v[168:171], v[108:111]
	v_mfma_f32_16x16x32_bf16 v[104:107], v[208:211], v[168:171], v[104:107]
	v_mfma_f32_16x16x32_bf16 v[92:95], v[200:203], v[176:179], v[92:95]
	v_mfma_f32_16x16x32_bf16 v[88:91], v[208:211], v[176:179], v[88:91]
	v_mfma_f32_16x16x32_bf16 v[76:79], v[200:203], v[184:187], v[76:79]
	v_mfma_f32_16x16x32_bf16 v[72:75], v[208:211], v[184:187], v[72:75]
	v_mfma_f32_16x16x32_bf16 v[68:71], v[200:203], v[192:195], v[68:71]
	v_mfma_f32_16x16x32_bf16 v[64:67], v[208:211], v[192:195], v[64:67]
	s_setprio 0
	s_mov_b32 m0, s58
	v_lshl_add_u64 v[144:145], v[214:215], 0, s[10:11]
	s_barrier
	ds_read_b128 v[164:167], v150 offset:49152
	ds_read_b128 v[168:171], v150 offset:50176
	ds_read_b128 v[172:175], v150 offset:51200
	ds_read_b128 v[176:179], v150 offset:52224
	ds_read_b128 v[180:183], v150 offset:53248
	ds_read_b128 v[184:187], v150 offset:54272
	ds_read_b128 v[188:191], v150 offset:55296
	ds_read_b128 v[192:195], v150 offset:56320
	global_load_lds_dwordx4 v[144:145], off
	v_lshl_add_u64 v[144:145], v[218:219], 0, s[10:11]
	s_mov_b32 m0, s59
	s_nop 0
	global_load_lds_dwordx4 v[144:145], off
	s_barrier
	s_waitcnt lgkmcnt(0)
	s_setprio 1
	s_waitcnt lgkmcnt(0)
	v_mfma_f32_16x16x32_bf16 v[60:63], v[140:143], v[164:167], v[60:63]
	v_mfma_f32_16x16x32_bf16 v[56:59], v[156:159], v[164:167], v[56:59]
	v_mfma_f32_16x16x32_bf16 v[52:55], v[140:143], v[172:175], v[52:55]
	v_mfma_f32_16x16x32_bf16 v[48:51], v[156:159], v[172:175], v[48:51]
	v_mfma_f32_16x16x32_bf16 v[40:43], v[140:143], v[180:183], v[40:43]
	v_mfma_f32_16x16x32_bf16 v[32:35], v[156:159], v[180:183], v[32:35]
	v_mfma_f32_16x16x32_bf16 v[24:27], v[140:143], v[188:191], v[24:27]
	v_mfma_f32_16x16x32_bf16 v[16:19], v[156:159], v[188:191], v[16:19]
	v_mfma_f32_16x16x32_bf16 v[60:63], v[152:155], v[168:171], v[60:63]
	v_mfma_f32_16x16x32_bf16 v[56:59], v[160:163], v[168:171], v[56:59]
	v_mfma_f32_16x16x32_bf16 v[52:55], v[152:155], v[176:179], v[52:55]
	v_mfma_f32_16x16x32_bf16 v[48:51], v[160:163], v[176:179], v[48:51]
	v_mfma_f32_16x16x32_bf16 v[40:43], v[152:155], v[184:187], v[40:43]
	v_mfma_f32_16x16x32_bf16 v[32:35], v[160:163], v[184:187], v[32:35]
	v_mfma_f32_16x16x32_bf16 v[24:27], v[152:155], v[192:195], v[24:27]
	v_mfma_f32_16x16x32_bf16 v[16:19], v[160:163], v[192:195], v[16:19]
	s_setprio 0
	s_barrier
	s_add_u32 s42, s42, 0x80080
	s_addc_u32 s43, s43, 0
	s_add_i32 s44, s44, s49
	v_lshl_add_u64 v[140:141], s[42:43], 0, v[128:129]
	s_mov_b32 m0, s44
	s_nop 0
	global_load_lds_dwordx4 v[140:141], off
	v_lshl_add_u64 v[140:141], s[42:43], 0, v[130:131]
	s_add_i32 m0, s44, 0x2000
	s_nop 0
	global_load_lds_dwordx4 v[140:141], off
	s_waitcnt vmcnt(6)
	s_barrier
	s_setprio 1
	v_mfma_f32_16x16x32_bf16 v[44:47], v[196:199], v[164:167], v[44:47]
	v_mfma_f32_16x16x32_bf16 v[36:39], v[204:207], v[164:167], v[36:39]
	v_mfma_f32_16x16x32_bf16 v[28:31], v[196:199], v[172:175], v[28:31]
	v_mfma_f32_16x16x32_bf16 v[20:23], v[204:207], v[172:175], v[20:23]
	v_mfma_f32_16x16x32_bf16 v[12:15], v[196:199], v[180:183], v[12:15]
	v_mfma_f32_16x16x32_bf16 v[8:11], v[204:207], v[180:183], v[8:11]
	v_mfma_f32_16x16x32_bf16 v[4:7], v[196:199], v[188:191], v[4:7]
	v_mfma_f32_16x16x32_bf16 v[0:3], v[204:207], v[188:191], v[0:3]
	v_mfma_f32_16x16x32_bf16 v[44:47], v[200:203], v[168:171], v[44:47]
	v_mfma_f32_16x16x32_bf16 v[36:39], v[208:211], v[168:171], v[36:39]
	v_mfma_f32_16x16x32_bf16 v[28:31], v[200:203], v[176:179], v[28:31]
	v_mfma_f32_16x16x32_bf16 v[20:23], v[208:211], v[176:179], v[20:23]
	v_mfma_f32_16x16x32_bf16 v[12:15], v[200:203], v[184:187], v[12:15]
	v_mfma_f32_16x16x32_bf16 v[8:11], v[208:211], v[184:187], v[8:11]
	v_mfma_f32_16x16x32_bf16 v[4:7], v[200:203], v[192:195], v[4:7]
	v_mfma_f32_16x16x32_bf16 v[0:3], v[208:211], v[192:195], v[0:3]
	s_setprio 0
	s_add_u32 s40, s40, 0x100
	s_addc_u32 s41, s41, 0
	s_add_u32 s76, s76, 0x100
	s_addc_u32 s77, s77, 0
	s_cmp_ge_i32 s78, s73
	s_mov_b32 s42, s78
	s_barrier
	s_cbranch_scc0 .LBB0_2585
	s_lshl_b32 s29, s4, 8
	v_mov_b32_e32 v140, v147
	v_mov_b32_e32 v141, v146
	s_add_i32 s29, s29, s56
	s_nop 0
	v_add_u32_e32 v142, s29, v141
	s_lshl_b32 s29, s38, 8
	s_or_b32 s29, s29, s57
	v_lshl_add_u32 v140, v140, 2, s29
	s_mov_b64 s[38:39], -1
	s_cmp_eq_u32 s4, 32
	v_ashrrev_i32_e32 v143, 31, v142
	v_ashrrev_i32_e32 v141, 31, v140
	s_cbranch_scc1 .LBB0_2588
	v_lshlrev_b64 v[144:145], 14, v[142:143]
	v_max_f32_e32 v152, 0, v124
	v_max_f32_e32 v153, 0, v125
	v_max_f32_e32 v154, 0, v126
	v_max_f32_e32 v155, 0, v127
	v_pk_mul_f32 v[152:153], v[152:153], v[152:153]
	v_pk_mul_f32 v[154:155], v[154:155], v[154:155]
	v_cvt_pk_bf16_f32 v152, v152, v153
	v_cvt_pk_bf16_f32 v153, v154, v155
	v_lshl_add_u64 v[144:145], s[8:9], 0, v[144:145]
	v_lshl_add_u64 v[144:145], v[140:141], 1, v[144:145]
	global_store_dwordx2 v[144:145], v[152:153], off
	v_max_f32_e32 v152, 0, v120
	v_max_f32_e32 v153, 0, v121
	v_max_f32_e32 v154, 0, v122
	v_max_f32_e32 v155, 0, v123
	v_pk_mul_f32 v[152:153], v[152:153], v[152:153]
	v_pk_mul_f32 v[154:155], v[154:155], v[154:155]
	v_cvt_pk_bf16_f32 v152, v152, v153
	v_cvt_pk_bf16_f32 v153, v154, v155
	global_store_dwordx2 v[144:145], v[152:153], off offset:32
	v_max_f32_e32 v152, 0, v108
	v_max_f32_e32 v153, 0, v109
	v_max_f32_e32 v154, 0, v110
	v_max_f32_e32 v155, 0, v111
	v_pk_mul_f32 v[152:153], v[152:153], v[152:153]
	v_pk_mul_f32 v[154:155], v[154:155], v[154:155]
	v_cvt_pk_bf16_f32 v152, v152, v153
	v_cvt_pk_bf16_f32 v153, v154, v155
	global_store_dwordx2 v[144:145], v[152:153], off offset:256
	v_max_f32_e32 v152, 0, v104
	v_max_f32_e32 v153, 0, v105
	v_max_f32_e32 v154, 0, v106
	v_max_f32_e32 v155, 0, v107
	v_pk_mul_f32 v[152:153], v[152:153], v[152:153]
	v_pk_mul_f32 v[154:155], v[154:155], v[154:155]
	v_cvt_pk_bf16_f32 v152, v152, v153
	v_cvt_pk_bf16_f32 v153, v154, v155
	global_store_dwordx2 v[144:145], v[152:153], off offset:288
	v_max_f32_e32 v152, 0, v116
	v_max_f32_e32 v153, 0, v117
	v_max_f32_e32 v154, 0, v118
	v_max_f32_e32 v155, 0, v119
	v_pk_mul_f32 v[152:153], v[152:153], v[152:153]
	v_pk_mul_f32 v[154:155], v[154:155], v[154:155]
	v_cvt_pk_bf16_f32 v152, v152, v153
	v_cvt_pk_bf16_f32 v153, v154, v155
	v_add_co_u32_e32 v154, vcc, s66, v144
	s_nop 1
	s_nop 1
	v_addc_co_u32_e32 v155, vcc, 0, v145, vcc
	global_store_dwordx2 v[154:155], v[152:153], off
	v_max_f32_e32 v152, 0, v112
	v_max_f32_e32 v153, 0, v113
	v_max_f32_e32 v154, 0, v114
	v_max_f32_e32 v155, 0, v115
	v_pk_mul_f32 v[152:153], v[152:153], v[152:153]
	v_pk_mul_f32 v[154:155], v[154:155], v[154:155]
	v_cvt_pk_bf16_f32 v152, v152, v153
	v_cvt_pk_bf16_f32 v153, v154, v155
	v_lshl_add_u64 v[156:157], v[144:145], 0, s[12:13]
	global_store_dwordx2 v[156:157], v[152:153], off offset:32
	v_max_f32_e32 v152, 0, v92
	v_max_f32_e32 v153, 0, v93
	v_max_f32_e32 v154, 0, v94
	v_max_f32_e32 v155, 0, v95
	v_pk_mul_f32 v[152:153], v[152:153], v[152:153]
	v_pk_mul_f32 v[154:155], v[154:155], v[154:155]
	v_cvt_pk_bf16_f32 v152, v152, v153
	v_cvt_pk_bf16_f32 v153, v154, v155
	global_store_dwordx2 v[156:157], v[152:153], off offset:256
	v_max_f32_e32 v152, 0, v88
	v_max_f32_e32 v153, 0, v89
	v_max_f32_e32 v154, 0, v90
	v_max_f32_e32 v155, 0, v91
	v_pk_mul_f32 v[152:153], v[152:153], v[152:153]
	v_pk_mul_f32 v[154:155], v[154:155], v[154:155]
	v_cvt_pk_bf16_f32 v152, v152, v153
	v_cvt_pk_bf16_f32 v153, v154, v155
	global_store_dwordx2 v[156:157], v[152:153], off offset:288
	v_max_f32_e32 v152, 0, v100
	v_max_f32_e32 v153, 0, v101
	v_max_f32_e32 v154, 0, v102
	v_max_f32_e32 v155, 0, v103
	v_pk_mul_f32 v[152:153], v[152:153], v[152:153]
	v_pk_mul_f32 v[154:155], v[154:155], v[154:155]
	v_cvt_pk_bf16_f32 v152, v152, v153
	v_cvt_pk_bf16_f32 v153, v154, v155
	v_add_co_u32_e32 v154, vcc, s67, v144
	s_nop 1
	s_nop 1
	v_addc_co_u32_e32 v155, vcc, 0, v145, vcc
	global_store_dwordx2 v[154:155], v[152:153], off
	v_max_f32_e32 v152, 0, v96
	v_max_f32_e32 v153, 0, v97
	v_max_f32_e32 v154, 0, v98
	v_max_f32_e32 v155, 0, v99
	v_pk_mul_f32 v[152:153], v[152:153], v[152:153]
	v_pk_mul_f32 v[154:155], v[154:155], v[154:155]
	v_cvt_pk_bf16_f32 v152, v152, v153
	v_cvt_pk_bf16_f32 v153, v154, v155
	v_lshl_add_u64 v[156:157], v[144:145], 0, s[6:7]
	global_store_dwordx2 v[156:157], v[152:153], off offset:32
	v_max_f32_e32 v152, 0, v76
	v_max_f32_e32 v153, 0, v77
	v_max_f32_e32 v154, 0, v78
	v_max_f32_e32 v155, 0, v79
	v_pk_mul_f32 v[152:153], v[152:153], v[152:153]
	v_pk_mul_f32 v[154:155], v[154:155], v[154:155]
	v_cvt_pk_bf16_f32 v152, v152, v153
	v_cvt_pk_bf16_f32 v153, v154, v155
	global_store_dwordx2 v[156:157], v[152:153], off offset:256
	v_max_f32_e32 v152, 0, v72
	v_max_f32_e32 v153, 0, v73
	v_max_f32_e32 v154, 0, v74
	v_max_f32_e32 v155, 0, v75
	v_pk_mul_f32 v[152:153], v[152:153], v[152:153]
	v_pk_mul_f32 v[154:155], v[154:155], v[154:155]
	v_cvt_pk_bf16_f32 v152, v152, v153
	v_cvt_pk_bf16_f32 v153, v154, v155
	global_store_dwordx2 v[156:157], v[152:153], off offset:288
	v_max_f32_e32 v152, 0, v84
	v_max_f32_e32 v153, 0, v85
	v_max_f32_e32 v154, 0, v86
	v_max_f32_e32 v155, 0, v87
	v_pk_mul_f32 v[152:153], v[152:153], v[152:153]
	v_pk_mul_f32 v[154:155], v[154:155], v[154:155]
	v_cvt_pk_bf16_f32 v152, v152, v153
	v_cvt_pk_bf16_f32 v153, v154, v155
	v_add_co_u32_e32 v154, vcc, s68, v144
	s_nop 1
	s_nop 1
	v_addc_co_u32_e32 v155, vcc, 0, v145, vcc
	global_store_dwordx2 v[154:155], v[152:153], off
	v_max_f32_e32 v152, 0, v80
	v_max_f32_e32 v153, 0, v81
	v_max_f32_e32 v154, 0, v82
	v_max_f32_e32 v155, 0, v83
	v_pk_mul_f32 v[152:153], v[152:153], v[152:153]
	v_pk_mul_f32 v[154:155], v[154:155], v[154:155]
	v_cvt_pk_bf16_f32 v152, v152, v153
	v_cvt_pk_bf16_f32 v153, v154, v155
	v_lshl_add_u64 v[156:157], v[144:145], 0, s[14:15]
	global_store_dwordx2 v[156:157], v[152:153], off offset:32
	v_max_f32_e32 v152, 0, v68
	v_max_f32_e32 v153, 0, v69
	v_max_f32_e32 v154, 0, v70
	v_max_f32_e32 v155, 0, v71
	v_pk_mul_f32 v[152:153], v[152:153], v[152:153]
	v_pk_mul_f32 v[154:155], v[154:155], v[154:155]
	v_cvt_pk_bf16_f32 v152, v152, v153
	v_cvt_pk_bf16_f32 v153, v154, v155
	global_store_dwordx2 v[156:157], v[152:153], off offset:256
	v_max_f32_e32 v152, 0, v64
	v_max_f32_e32 v153, 0, v65
	v_max_f32_e32 v154, 0, v66
	v_max_f32_e32 v155, 0, v67
	v_pk_mul_f32 v[152:153], v[152:153], v[152:153]
	v_pk_mul_f32 v[154:155], v[154:155], v[154:155]
	v_cvt_pk_bf16_f32 v152, v152, v153
	v_cvt_pk_bf16_f32 v153, v154, v155
	global_store_dwordx2 v[156:157], v[152:153], off offset:288
	v_max_f32_e32 v152, 0, v60
	v_max_f32_e32 v153, 0, v61
	v_max_f32_e32 v154, 0, v62
	v_max_f32_e32 v155, 0, v63
	v_pk_mul_f32 v[152:153], v[152:153], v[152:153]
	v_pk_mul_f32 v[154:155], v[154:155], v[154:155]
	v_cvt_pk_bf16_f32 v152, v152, v153
	v_cvt_pk_bf16_f32 v153, v154, v155
	v_add_co_u32_e32 v154, vcc, s69, v144
	s_nop 1
	s_nop 1
	v_addc_co_u32_e32 v155, vcc, 0, v145, vcc
	global_store_dwordx2 v[154:155], v[152:153], off
	v_max_f32_e32 v152, 0, v56
	v_max_f32_e32 v153, 0, v57
	v_max_f32_e32 v154, 0, v58
	v_max_f32_e32 v155, 0, v59
	v_pk_mul_f32 v[152:153], v[152:153], v[152:153]
	v_pk_mul_f32 v[154:155], v[154:155], v[154:155]
	v_cvt_pk_bf16_f32 v152, v152, v153
	v_cvt_pk_bf16_f32 v153, v154, v155
	v_lshl_add_u64 v[156:157], v[144:145], 0, s[16:17]
	global_store_dwordx2 v[156:157], v[152:153], off offset:32
	v_max_f32_e32 v152, 0, v44
	v_max_f32_e32 v153, 0, v45
	v_max_f32_e32 v154, 0, v46
	v_max_f32_e32 v155, 0, v47
	v_pk_mul_f32 v[152:153], v[152:153], v[152:153]
	v_pk_mul_f32 v[154:155], v[154:155], v[154:155]
	v_cvt_pk_bf16_f32 v152, v152, v153
	v_cvt_pk_bf16_f32 v153, v154, v155
	global_store_dwordx2 v[156:157], v[152:153], off offset:256
	v_max_f32_e32 v152, 0, v36
	v_max_f32_e32 v153, 0, v37
	v_max_f32_e32 v154, 0, v38
	v_max_f32_e32 v155, 0, v39
	v_pk_mul_f32 v[152:153], v[152:153], v[152:153]
	v_pk_mul_f32 v[154:155], v[154:155], v[154:155]
	v_cvt_pk_bf16_f32 v152, v152, v153
	v_cvt_pk_bf16_f32 v153, v154, v155
	global_store_dwordx2 v[156:157], v[152:153], off offset:288
	v_max_f32_e32 v152, 0, v52
	v_max_f32_e32 v153, 0, v53
	v_max_f32_e32 v154, 0, v54
	v_max_f32_e32 v155, 0, v55
	v_pk_mul_f32 v[152:153], v[152:153], v[152:153]
	v_pk_mul_f32 v[154:155], v[154:155], v[154:155]
	v_cvt_pk_bf16_f32 v152, v152, v153
	v_cvt_pk_bf16_f32 v153, v154, v155
	v_add_co_u32_e32 v154, vcc, s70, v144
	s_nop 1
	s_nop 1
	v_addc_co_u32_e32 v155, vcc, 0, v145, vcc
	global_store_dwordx2 v[154:155], v[152:153], off
	v_max_f32_e32 v152, 0, v48
	v_max_f32_e32 v153, 0, v49
	v_max_f32_e32 v154, 0, v50
	v_max_f32_e32 v155, 0, v51
	v_pk_mul_f32 v[152:153], v[152:153], v[152:153]
	v_pk_mul_f32 v[154:155], v[154:155], v[154:155]
	v_cvt_pk_bf16_f32 v152, v152, v153
	v_cvt_pk_bf16_f32 v153, v154, v155
	v_lshl_add_u64 v[156:157], v[144:145], 0, s[18:19]
	global_store_dwordx2 v[156:157], v[152:153], off offset:32
	v_max_f32_e32 v152, 0, v28
	v_max_f32_e32 v153, 0, v29
	v_max_f32_e32 v154, 0, v30
	v_max_f32_e32 v155, 0, v31
	v_pk_mul_f32 v[152:153], v[152:153], v[152:153]
	v_pk_mul_f32 v[154:155], v[154:155], v[154:155]
	v_cvt_pk_bf16_f32 v152, v152, v153
	v_cvt_pk_bf16_f32 v153, v154, v155
	global_store_dwordx2 v[156:157], v[152:153], off offset:256
	v_max_f32_e32 v152, 0, v20
	v_max_f32_e32 v153, 0, v21
	v_max_f32_e32 v154, 0, v22
	v_max_f32_e32 v155, 0, v23
	v_pk_mul_f32 v[152:153], v[152:153], v[152:153]
	v_pk_mul_f32 v[154:155], v[154:155], v[154:155]
	v_cvt_pk_bf16_f32 v152, v152, v153
	v_cvt_pk_bf16_f32 v153, v154, v155
	global_store_dwordx2 v[156:157], v[152:153], off offset:288
	v_max_f32_e32 v152, 0, v40
	v_max_f32_e32 v153, 0, v41
	v_max_f32_e32 v154, 0, v42
	v_max_f32_e32 v155, 0, v43
	v_pk_mul_f32 v[152:153], v[152:153], v[152:153]
	v_pk_mul_f32 v[154:155], v[154:155], v[154:155]
	v_cvt_pk_bf16_f32 v152, v152, v153
	v_cvt_pk_bf16_f32 v153, v154, v155
	v_add_co_u32_e32 v154, vcc, s71, v144
	s_nop 1
	s_nop 1
	v_addc_co_u32_e32 v155, vcc, 0, v145, vcc
	global_store_dwordx2 v[154:155], v[152:153], off
	v_max_f32_e32 v152, 0, v32
	v_max_f32_e32 v153, 0, v33
	v_max_f32_e32 v154, 0, v34
	v_max_f32_e32 v155, 0, v35
	v_pk_mul_f32 v[152:153], v[152:153], v[152:153]
	v_pk_mul_f32 v[154:155], v[154:155], v[154:155]
	v_cvt_pk_bf16_f32 v152, v152, v153
	v_cvt_pk_bf16_f32 v153, v154, v155
	v_lshl_add_u64 v[156:157], v[144:145], 0, s[20:21]
	global_store_dwordx2 v[156:157], v[152:153], off offset:32
	v_max_f32_e32 v152, 0, v12
	v_max_f32_e32 v153, 0, v13
	v_max_f32_e32 v154, 0, v14
	v_max_f32_e32 v155, 0, v15
	v_pk_mul_f32 v[152:153], v[152:153], v[152:153]
	v_pk_mul_f32 v[154:155], v[154:155], v[154:155]
	v_cvt_pk_bf16_f32 v152, v152, v153
	v_cvt_pk_bf16_f32 v153, v154, v155
	global_store_dwordx2 v[156:157], v[152:153], off offset:256
	v_max_f32_e32 v152, 0, v8
	v_max_f32_e32 v153, 0, v9
	v_max_f32_e32 v154, 0, v10
	v_max_f32_e32 v155, 0, v11
	v_pk_mul_f32 v[152:153], v[152:153], v[152:153]
	v_pk_mul_f32 v[154:155], v[154:155], v[154:155]
	v_cvt_pk_bf16_f32 v152, v152, v153
	v_cvt_pk_bf16_f32 v153, v154, v155
	global_store_dwordx2 v[156:157], v[152:153], off offset:288
	v_max_f32_e32 v152, 0, v24
	v_max_f32_e32 v153, 0, v25
	v_max_f32_e32 v154, 0, v26
	v_max_f32_e32 v155, 0, v27
	v_pk_mul_f32 v[152:153], v[152:153], v[152:153]
	v_pk_mul_f32 v[154:155], v[154:155], v[154:155]
	v_cvt_pk_bf16_f32 v152, v152, v153
	v_cvt_pk_bf16_f32 v153, v154, v155
	v_lshl_add_u64 v[156:157], v[144:145], 0, s[22:23]
	v_add_co_u32_e32 v144, vcc, s72, v144
	s_nop 1
	v_addc_co_u32_e32 v145, vcc, 0, v145, vcc
	global_store_dwordx2 v[144:145], v[152:153], off
	v_max_f32_e32 v144, 0, v16
	v_max_f32_e32 v145, 0, v17
	v_max_f32_e32 v152, 0, v18
	v_max_f32_e32 v153, 0, v19
	v_pk_mul_f32 v[144:145], v[144:145], v[144:145]
	v_pk_mul_f32 v[152:153], v[152:153], v[152:153]
	v_cvt_pk_bf16_f32 v144, v144, v145
	v_cvt_pk_bf16_f32 v145, v152, v153
	global_store_dwordx2 v[156:157], v[144:145], off offset:32
	v_max_f32_e32 v144, 0, v4
	v_max_f32_e32 v145, 0, v5
	v_max_f32_e32 v152, 0, v6
	v_max_f32_e32 v153, 0, v7
	v_pk_mul_f32 v[144:145], v[144:145], v[144:145]
	v_pk_mul_f32 v[152:153], v[152:153], v[152:153]
	v_cvt_pk_bf16_f32 v144, v144, v145
	v_cvt_pk_bf16_f32 v145, v152, v153
	global_store_dwordx2 v[156:157], v[144:145], off offset:256
	v_max_f32_e32 v144, 0, v0
	v_max_f32_e32 v145, 0, v1
	v_max_f32_e32 v152, 0, v2
	v_max_f32_e32 v153, 0, v3
	v_pk_mul_f32 v[144:145], v[144:145], v[144:145]
	v_pk_mul_f32 v[152:153], v[152:153], v[152:153]
	v_cvt_pk_bf16_f32 v144, v144, v145
	v_cvt_pk_bf16_f32 v145, v152, v153
	s_mov_b64 s[38:39], 0
	global_store_dwordx2 v[156:157], v[144:145], off offset:288
